# stick-breaking per-wave loop: separate iteration body for off-diagonal key tiles without the branch-free diagonal masking (63 VALU fewer per tile)
# speedup vs baseline: 1.0081x; 1.0081x over previous
; #define LAS __attribute__((address_space(3)))
; #define WSYNC() asm volatile("s_waitcnt lgkmcnt(0)" ::: "memory")
; __device__ __forceinline__ int crow(int r, int hi) { return (r & 3) + 8 * (r >> 2) + 4 * hi; }
; #define MFMA32(a, b, c) __builtin_amdgcn_mfma_f32_32x32x16_bf16((a), (b), (c), 0, 0, 0)
; __device__ __forceinline__ void sb_wave(int bh, int qblk, int lane, const bf16_t* __restrict__ P1, const bf16_t* __restrict__ VT, bf16_t* __restrict__ ymix, LAS unsigned char* wl) {
;     ...
;         for (int i = 0; i < 4; ++i) { *(LAS v4u*)(wl + lK + i * 8 * 144) = rk[i]; *(LAS u32x2*)(wl + lV + i * 16 * 72) = (u32x2){rv[i].x, rv[i].y}; *(LAS u32x2*)(wl + lV + i * 16 * 72 + 8) = (u32x2){rv[i].z, rv[i].w}; }
;         { const int sn = (s0 >= 32) ? s0 - 32 : 0;
; #pragma unroll
;           for (int i = 0; i < 4; ++i) { rk[i] = *(const v4u*)(gK + (size_t)(sn + 8 * i) * L1P); rv[i] = *(const v4u*)(gV + (size_t)(16 * i) * M + sn); } }
;         WSYNC();
;         f32x16 acc;
; #pragma unroll
;         for (int r = 0; r < 16; ++r) acc[r] = 0.f;
; #pragma unroll
;         for (int kk = 0; kk < 4; ++kk) { const bf16x8 kf = *(const LAS bf16x8*)(wl + l31 * 144 + (16 * kk + 8 * hi) * 2); acc = MFMA32(kf, qf[kk], acc); }
;         const bool diag = (s0 == q0);
;         float bt[16], kp[16];
; #pragma unroll
;         for (int r = 0; r < 16; ++r) { const float ee = __builtin_amdgcn_exp2f(fminf(acc[r] * (-0.125f * 1.4426950408889634f), 100.f)); const float ri = __builtin_amdgcn_rcpf(1.f + ee);
;             float b_ = ri, k_ = ee * ri;
;             if (diag) { const bool valid = (s0 + crow(r, hi)) < t; b_ = valid ? b_ : 0.f; k_ = valid ? k_ : 1.f; }
;             bt[r] = b_; kp[r] = k_; }
.LBB0_1570:
	s_waitcnt vmcnt(0)
	s_cmp_eq_u32 s19, 0
	s_cbranch_scc0 .Lsb_nd_body
	ds_write_b128 v119, v[46:49]
	v_add_u32_e32 v46, 0x1200, v120
	ds_write2_b64 v46, v[34:35], v[36:37] offset1:1
	ds_write_b128 v119, v[70:73] offset:1152
	v_add_u32_e32 v34, 0x1680, v120
	ds_write2_b64 v34, v[42:43], v[44:45] offset1:1
	ds_write_b128 v119, v[66:69] offset:2304
	v_add_u32_e32 v34, 0x1b00, v120
	ds_write2_b64 v34, v[38:39], v[40:41] offset1:1
	ds_write_b128 v119, v[78:81] offset:3456
	v_add_u32_e32 v34, 0x1f80, v120
	ds_write2_b64 v34, v[74:75], v[76:77] offset1:1
	s_waitcnt lgkmcnt(0)
	v_add_u32_e32 v70, v87, v86
	ds_read_b128 v[34:37], v70
	ds_read_b128 v[66:69], v70 offset:32
	s_waitcnt lgkmcnt(1)
	v_mfma_f32_32x32x16_bf16 v[34:49], v[34:37], v[50:53], 0
	s_cmp_eq_u32 s19, 0
	s_mov_b64 s[48:49], -1
	s_waitcnt lgkmcnt(0)
	v_mfma_f32_32x32x16_bf16 v[34:49], v[66:69], v[54:57], v[34:49]
	ds_read_b128 v[66:69], v70 offset:64
	ds_read_b128 v[70:73], v70 offset:96
	s_waitcnt lgkmcnt(1)
	v_mfma_f32_32x32x16_bf16 v[34:49], v[66:69], v[58:61], v[34:49]
	v_add_u32_e32 v66, s19, v99
	v_add_u32_e32 v67, 1, v66
	v_add_u32_e32 v68, 2, v66
	v_cmp_lt_i32_e64 s[12:13], v67, v97
	v_cmp_lt_i32_e32 vcc, v66, v97
	s_waitcnt lgkmcnt(0)
	v_mfma_f32_32x32x16_bf16 v[34:49], v[70:73], v[62:65], v[34:49]
	s_nop 11
	v_mul_f32_e32 v35, 0xbe38aa3b, v35
	v_mul_f32_e32 v34, 0xbe38aa3b, v34
	v_min_f32_e32 v35, 0x42c80000, v35
	v_mul_f32_e32 v36, 0xbe38aa3b, v36
	v_min_f32_e32 v34, 0x42c80000, v34
	v_exp_f32_e32 v35, v35
	v_min_f32_e32 v36, 0x42c80000, v36
	v_exp_f32_e32 v34, v34
	v_exp_f32_e32 v36, v36
	v_mul_f32_e32 v37, 0xbe38aa3b, v37
	v_min_f32_e32 v37, 0x42c80000, v37
	v_add_f32_e32 v70, 1.0, v35
	v_exp_f32_e32 v69, v37
	v_add_f32_e32 v37, 1.0, v34
	v_rcp_f32_e32 v70, v70
	v_rcp_f32_e32 v37, v37
	v_add_f32_e32 v71, 1.0, v36
	v_rcp_f32_e32 v71, v71
	v_mul_f32_e32 v38, 0xbe38aa3b, v38
	v_min_f32_e32 v38, 0x42c80000, v38
	v_mul_f32_e32 v73, v35, v70
	v_exp_f32_e32 v38, v38
	v_mul_f32_e32 v34, v34, v37
	v_cndmask_b32_e64 v67, 0, v70, s[12:13]
	v_cndmask_b32_e64 v74, 1.0, v73, s[12:13]
	v_cmp_lt_i32_e64 s[12:13], v68, v97
	v_add_f32_e32 v68, 1.0, v69
	v_cndmask_b32_e32 v72, 0, v37, vcc
	v_mul_f32_e32 v36, v36, v71
	v_cndmask_b32_e32 v35, 1.0, v34, vcc
	s_cselect_b64 vcc, -1, 0
	v_rcp_f32_e32 v68, v68
	v_cndmask_b32_e32 v35, v34, v35, vcc
	v_cndmask_b32_e32 v67, v70, v67, vcc
	v_cndmask_b32_e64 v34, 0, v71, s[12:13]
	v_cndmask_b32_e64 v70, 1.0, v36, s[12:13]
	v_cndmask_b32_e32 v36, v36, v70, vcc
	v_cndmask_b32_e32 v70, v71, v34, vcc
	v_add_f32_e32 v71, 1.0, v38
	v_rcp_f32_e32 v71, v71
	v_mul_f32_e32 v34, v69, v68
	v_add_u32_e32 v69, 3, v66
	v_cmp_lt_i32_e64 s[12:13], v69, v97
	v_cndmask_b32_e32 v72, v37, v72, vcc
	v_cndmask_b32_e32 v37, v73, v74, vcc
	v_cndmask_b32_e64 v73, 1.0, v34, s[12:13]
	v_cndmask_b32_e32 v73, v34, v73, vcc
	v_mul_f32_e32 v34, v38, v71
	v_mul_f32_e32 v38, 0xbe38aa3b, v39
	v_min_f32_e32 v38, 0x42c80000, v38
	v_exp_f32_e32 v38, v38
	v_add_u32_e32 v39, 8, v66
	v_cndmask_b32_e64 v69, 0, v68, s[12:13]
	v_cmp_lt_i32_e64 s[12:13], v39, v97
	v_cndmask_b32_e32 v68, v68, v69, vcc
	v_add_f32_e32 v69, 1.0, v38
	v_cndmask_b32_e64 v39, 0, v71, s[12:13]
	v_cndmask_b32_e32 v71, v71, v39, vcc
	v_mul_f32_e32 v39, 0xbe38aa3b, v40
	v_min_f32_e32 v39, 0x42c80000, v39
	v_rcp_f32_e32 v69, v69
	v_exp_f32_e32 v39, v39
	v_mul_f32_e32 v41, 0xbe38aa3b, v41
	v_min_f32_e32 v41, 0x42c80000, v41
	v_exp_f32_e32 v41, v41
	v_cndmask_b32_e64 v74, 1.0, v34, s[12:13]
	v_add_u32_e32 v40, 9, v66
	v_cndmask_b32_e32 v34, v34, v74, vcc
	v_mul_f32_e32 v38, v38, v69
	v_cmp_lt_i32_e64 s[12:13], v40, v97
	v_add_f32_e32 v74, 1.0, v39
	v_rcp_f32_e32 v74, v74
	v_cndmask_b32_e64 v75, 1.0, v38, s[12:13]
	v_cndmask_b32_e32 v38, v38, v75, vcc
	v_add_f32_e32 v75, 1.0, v41
	v_cndmask_b32_e64 v40, 0, v69, s[12:13]
	v_rcp_f32_e32 v75, v75
	v_cndmask_b32_e32 v40, v69, v40, vcc
	v_add_u32_e32 v69, 10, v66
	v_mul_f32_e32 v39, v39, v74
	v_cmp_lt_i32_e64 s[12:13], v69, v97
	s_nop 1
	v_cndmask_b32_e64 v76, 1.0, v39, s[12:13]
	v_cndmask_b32_e32 v76, v39, v76, vcc
	v_mul_f32_e32 v39, v41, v75
	v_mul_f32_e32 v41, 0xbe38aa3b, v42
	v_min_f32_e32 v41, 0x42c80000, v41
	v_exp_f32_e32 v41, v41
	v_cndmask_b32_e64 v69, 0, v74, s[12:13]
	v_cndmask_b32_e32 v69, v74, v69, vcc
	v_add_u32_e32 v42, 11, v66
	v_add_f32_e32 v74, 1.0, v41
	v_rcp_f32_e32 v74, v74
	v_cmp_lt_i32_e64 s[12:13], v42, v97
	s_nop 1
	v_cndmask_b32_e64 v77, 1.0, v39, s[12:13]
	v_cndmask_b32_e32 v77, v39, v77, vcc
	v_mul_f32_e32 v39, v41, v74
	v_mul_f32_e32 v41, 0xbe38aa3b, v43
	v_min_f32_e32 v41, 0x42c80000, v41
	v_exp_f32_e32 v41, v41
	v_cndmask_b32_e64 v42, 0, v75, s[12:13]
	v_cndmask_b32_e32 v42, v75, v42, vcc
	v_add_u32_e32 v43, 16, v66
	v_add_f32_e32 v75, 1.0, v41
	v_rcp_f32_e32 v75, v75
	v_cmp_lt_i32_e64 s[12:13], v43, v97
	s_nop 1
	v_cndmask_b32_e64 v78, 1.0, v39, s[12:13]
	v_cndmask_b32_e32 v78, v39, v78, vcc
	v_mul_f32_e32 v39, v41, v75
	v_mul_f32_e32 v41, 0xbe38aa3b, v44
	v_min_f32_e32 v41, 0x42c80000, v41
	v_exp_f32_e32 v41, v41
	v_cndmask_b32_e64 v43, 0, v74, s[12:13]
	v_cndmask_b32_e32 v43, v74, v43, vcc
	v_add_u32_e32 v44, 17, v66
	v_add_f32_e32 v74, 1.0, v41
	v_rcp_f32_e32 v74, v74
	v_cmp_lt_i32_e64 s[12:13], v44, v97
	s_nop 1
	v_cndmask_b32_e64 v79, 1.0, v39, s[12:13]
	v_cndmask_b32_e32 v79, v39, v79, vcc
	v_mul_f32_e32 v39, v41, v74
	v_mul_f32_e32 v41, 0xbe38aa3b, v45
	v_min_f32_e32 v41, 0x42c80000, v41
	v_exp_f32_e32 v41, v41
	v_cndmask_b32_e64 v44, 0, v75, s[12:13]
	v_cndmask_b32_e32 v44, v75, v44, vcc
	v_add_u32_e32 v45, 18, v66
	v_add_f32_e32 v75, 1.0, v41
	v_rcp_f32_e32 v75, v75
	v_cmp_lt_i32_e64 s[12:13], v45, v97
	s_nop 1
; #define LAS __attribute__((address_space(3)))
; #define WSYNC() asm volatile("s_waitcnt lgkmcnt(0)" ::: "memory")
; __device__ __forceinline__ int crow(int r, int hi) { return (r & 3) + 8 * (r >> 2) + 4 * hi; }
; #define MFMA32(a, b, c) __builtin_amdgcn_mfma_f32_32x32x16_bf16((a), (b), (c), 0, 0, 0)
; __device__ __forceinline__ void sb_wave(int bh, int qblk, int lane, const bf16_t* __restrict__ P1, const bf16_t* __restrict__ VT, bf16_t* __restrict__ ymix, LAS unsigned char* wl) {
;     ...
;             if (diag) { const bool valid = (s0 + crow(r, hi)) < t; b_ = valid ? b_ : 0.f; k_ = valid ? k_ : 1.f; }
;             bt[r] = b_; kp[r] = k_; }
;         float e[16], T[4], U[4];
; #pragma unroll
;         for (int q = 0; q < 4; ++q) { e[4 * q + 3] = 1.f; e[4 * q + 2] = kp[4 * q + 3]; e[4 * q + 1] = e[4 * q + 2] * kp[4 * q + 2]; e[4 * q] = e[4 * q + 1] * kp[4 * q + 1]; T[q] = e[4 * q] * kp[4 * q]; }
; #pragma unroll
;         for (int q = 0; q < 4; ++q) U[q] = xhalf(T[q], hi);
;         { const float st2 = T[3], st1 = st2 * T[2], st0 = st1 * T[1]; const float su2 = U[3], su1 = su2 * U[2], su0 = su1 * U[1];
;           const float x0 = hi ? 1.f : U[0], x1 = hi ? 1.f : U[1], x2 = hi ? 1.f : U[2], x3 = hi ? 1.f : U[3];
;           const float off[4] = {cum * (st0 * su0 * x0), cum * (st1 * su1 * x1), cum * (st2 * su2 * x2), cum * x3};
; #pragma unroll
;           for (int r = 0; r < 16; ++r) acc[r] = bt[r] * (off[r >> 2] * e[r]);
;           cum *= (st0 * T[0]) * (su0 * U[0]); }
;         bf16x8 pf[2];
; #pragma unroll
;         for (int ks = 0; ks < 2; ++ks) pf[ks] = pack8(acc[8 * ks], acc[8 * ks + 1], acc[8 * ks + 2], acc[8 * ks + 3], acc[8 * ks + 4], acc[8 * ks + 5], acc[8 * ks + 6], acc[8 * ks + 7]);
; #pragma unroll
;         for (int dt = 0; dt < 2; ++dt)
; #pragma unroll
;             for (int ks = 0; ks < 2; ++ks) { const LAS unsigned char* vp = wl + 4608 + (32 * dt + l31) * 72 + (16 * ks + 4 * hi) * 2;
;                 const u32x2 x0 = *(const LAS u32x2*)vp, x1 = *(const LAS u32x2*)(vp + 16);
;                 v4u a; a.x = x0.x; a.y = x0.y; a.z = x1.x; a.w = x1.y; o[dt] = MFMA32(__builtin_bit_cast(bf16x8, a), pf[ks], o[dt]); }
;         WSYNC();
;         if (__all(cum < 1e-35f)) break;
	v_cndmask_b32_e64 v80, 1.0, v39, s[12:13]
	v_cndmask_b32_e32 v80, v39, v80, vcc
	v_mul_f32_e32 v39, v41, v75
	v_mul_f32_e32 v41, 0xbe38aa3b, v46
	v_min_f32_e32 v41, 0x42c80000, v41
	v_exp_f32_e32 v41, v41
	v_cndmask_b32_e64 v45, 0, v74, s[12:13]
	v_cndmask_b32_e32 v45, v74, v45, vcc
	v_add_u32_e32 v46, 19, v66
	v_add_f32_e32 v74, 1.0, v41
	v_rcp_f32_e32 v74, v74
	v_cmp_lt_i32_e64 s[12:13], v46, v97
	s_nop 1
	v_cndmask_b32_e64 v81, 1.0, v39, s[12:13]
	v_cndmask_b32_e32 v81, v39, v81, vcc
	v_mul_f32_e32 v39, v41, v74
	v_mul_f32_e32 v41, 0xbe38aa3b, v47
	v_min_f32_e32 v41, 0x42c80000, v41
	v_exp_f32_e32 v41, v41
	v_cndmask_b32_e64 v46, 0, v75, s[12:13]
	v_cndmask_b32_e32 v46, v75, v46, vcc
	v_add_u32_e32 v47, 24, v66
	v_add_f32_e32 v75, 1.0, v41
	v_rcp_f32_e32 v75, v75
	v_cmp_lt_i32_e64 s[12:13], v47, v97
	s_nop 1
	v_cndmask_b32_e64 v104, 1.0, v39, s[12:13]
	v_cndmask_b32_e32 v104, v39, v104, vcc
	v_mul_f32_e32 v39, v41, v75
	v_mul_f32_e32 v41, 0xbe38aa3b, v48
	v_min_f32_e32 v41, 0x42c80000, v41
	v_exp_f32_e32 v41, v41
	v_cndmask_b32_e64 v47, 0, v74, s[12:13]
	v_cndmask_b32_e32 v74, v74, v47, vcc
	v_add_u32_e32 v47, 25, v66
	v_add_f32_e32 v48, 1.0, v41
	v_rcp_f32_e32 v48, v48
	v_cmp_lt_i32_e64 s[12:13], v47, v97
	s_nop 1
	v_cndmask_b32_e64 v125, 1.0, v39, s[12:13]
	v_cndmask_b32_e32 v125, v39, v125, vcc
	v_mul_f32_e32 v39, v41, v48
	v_mul_f32_e32 v41, 0xbe38aa3b, v49
	v_min_f32_e32 v41, 0x42c80000, v41
	v_exp_f32_e32 v41, v41
	v_cndmask_b32_e64 v47, 0, v75, s[12:13]
	v_cndmask_b32_e32 v75, v75, v47, vcc
	v_add_u32_e32 v47, 26, v66
	v_add_f32_e32 v49, 1.0, v41
	v_rcp_f32_e32 v49, v49
	v_cmp_lt_i32_e64 s[12:13], v47, v97
	s_nop 1
	v_cndmask_b32_e64 v126, 1.0, v39, s[12:13]
	v_cndmask_b32_e32 v126, v39, v126, vcc
	v_mul_f32_e32 v39, v41, v49
	v_add_u32_e32 v41, 27, v66
	v_cndmask_b32_e64 v47, 0, v48, s[12:13]
	v_cmp_lt_i32_e64 s[12:13], v41, v97
	v_cndmask_b32_e32 v127, v48, v47, vcc
	v_mul_f32_e32 v48, v81, v80
	v_cndmask_b32_e64 v41, 0, v49, s[12:13]
	v_cndmask_b32_e32 v128, v49, v41, vcc
	v_mul_f32_e32 v41, v77, v76
	v_cndmask_b32_e64 v47, 1.0, v39, s[12:13]
	v_mul_f32_e32 v76, v38, v41
	v_cndmask_b32_e32 v66, v39, v47, vcc
	v_mul_f32_e32 v47, v34, v76
	v_mul_f32_e32 v39, v73, v36
	v_mul_f32_e32 v49, v79, v48
	v_mov_b32_e32 v34, v47
	v_mov_b32_e32 v36, v47
	v_mul_f32_e32 v78, v78, v49
	v_mul_f32_e32 v79, v66, v126
	v_permlane32_swap_b32_e32 v34, v36
	v_mul_f32_e32 v80, v125, v79
	v_cndmask_b32_e64 v34, v34, v36, s[10:11]
	v_mov_b32_e32 v36, v78
	v_mov_b32_e32 v38, v78
	v_mul_f32_e32 v104, v104, v80
	s_nop 0
	v_permlane32_swap_b32_e32 v36, v38
	v_cndmask_b32_e64 v36, v36, v38, s[10:11]
	v_mov_b32_e32 v38, v104
	v_mov_b32_e32 v125, v104
	s_nop 1
	v_permlane32_swap_b32_e32 v38, v125
	v_cndmask_b32_e64 v38, v38, v125, s[10:11]
	v_mul_f32_e32 v78, v104, v78
	v_cndmask_b32_e64 v126, 1.0, v36, s[10:11]
	v_mul_f32_e32 v104, v104, v38
	v_mul_f32_e32 v104, v126, v104
	v_mul_f32_e32 v104, v101, v104
	v_cndmask_b32_e64 v129, 1.0, v38, s[10:11]
	v_mul_f32_e32 v49, v49, v104
	v_pk_mul_f32 v[36:37], v[36:37], v[38:39]
	v_mul_f32_e32 v126, v101, v129
	v_mul_f32_e32 v129, v43, v49
	v_mul_f32_e32 v43, v48, v104
	v_pk_mul_f32 v[48:49], v[36:37], v[34:35]
	v_cndmask_b32_e64 v125, 1.0, v34, s[10:11]
	v_mov_b32_e32 v34, v49
	v_mov_b32_e32 v35, v49
	s_nop 1
	v_permlane32_swap_b32_e32 v34, v35
	v_mul_f32_e32 v47, v47, v78
	v_mul_f32_e32 v130, v44, v43
	v_mul_f32_e32 v43, v81, v104
	v_mul_f32_e32 v104, v46, v104
	v_cndmask_b32_e64 v46, v34, v35, s[10:11]
	v_cndmask_b32_e64 v34, 1.0, v46, s[10:11]
	v_mul_f32_e32 v35, v48, v47
	v_mul_f32_e32 v34, v34, v35
	v_mul_f32_e32 v35, v36, v78
	v_mul_f32_e32 v81, v45, v43
	v_mul_f32_e32 v43, v126, v80
	v_mul_f32_e32 v34, v101, v34
	v_mul_f32_e32 v35, v125, v35
	v_mul_f32_e32 v74, v74, v43
	v_mul_f32_e32 v43, v126, v79
	v_mul_f32_e32 v38, v101, v35
	v_mul_f32_e32 v35, v37, v34
	v_mul_f32_e32 v75, v75, v43
	v_mul_f32_e32 v43, v72, v35
	v_mul_f32_e32 v35, v39, v34
	v_mul_f32_e32 v39, v67, v35
	v_mul_f32_e32 v35, v73, v34
	v_mul_f32_e32 v45, v68, v34
	v_mul_f32_e32 v34, v76, v38
	v_mul_f32_e32 v67, v71, v34
	v_mul_f32_e32 v34, v41, v38
	v_add_u32_e32 v68, 0x1000, v121
	v_mul_f32_e32 v44, v70, v35
	v_mul_f32_e32 v40, v40, v34
	ds_read2_b64 v[34:37], v68 offset0:64 offset1:66
	v_mul_f32_e32 v41, v77, v38
	v_mul_f32_e32 v41, v69, v41
	v_mul_f32_e32 v42, v42, v38
	v_cvt_pk_bf16_f32 v38, v43, v39
	v_cvt_pk_bf16_f32 v39, v44, v45
	v_cvt_pk_bf16_f32 v40, v67, v40
	v_cvt_pk_bf16_f32 v41, v41, v42
	ds_read2_b64 v[42:45], v68 offset0:68 offset1:70
	s_mov_b64 s[12:13], -1
	s_waitcnt lgkmcnt(1)
	v_mfma_f32_32x32x16_bf16 v[18:33], v[34:37], v[38:41], v[18:33]
	v_mul_f32_e32 v34, v126, v66
	v_mul_f32_e32 v37, v127, v34
	v_mul_f32_e32 v66, v128, v126
	v_cvt_pk_bf16_f32 v34, v129, v130
	v_cvt_pk_bf16_f32 v35, v81, v104
	v_cvt_pk_bf16_f32 v36, v74, v75
	v_cvt_pk_bf16_f32 v37, v37, v66
	v_add_u32_e32 v66, 0x1000, v122
	s_waitcnt lgkmcnt(0)
	v_mfma_f32_32x32x16_bf16 v[18:33], v[42:45], v[34:37], v[18:33]
	ds_read2_b64 v[42:45], v66 offset0:64 offset1:66
	s_waitcnt lgkmcnt(0)
	v_mfma_f32_32x32x16_bf16 v[2:17], v[42:45], v[38:41], v[2:17]
	ds_read2_b64 v[38:41], v66 offset0:68 offset1:70
	v_mul_f32_e64 v42, v48, v46
	v_mul_f32_e64 v43, v49, v47
	s_waitcnt lgkmcnt(0)
	v_mul_f32_e32 v42, v42, v43
	v_mul_f32_e32 v101, v101, v42
	s_waitcnt lgkmcnt(0)
	v_mfma_f32_32x32x16_bf16 v[2:17], v[38:41], v[34:37], v[2:17]
	v_cmp_gt_f32_e32 vcc, s51, v101
	s_cmp_lg_u64 vcc, exec
	s_cbranch_scc0 .LBB0_1569
; #define LAS __attribute__((address_space(3)))
; #define WSYNC() asm volatile("s_waitcnt lgkmcnt(0)" ::: "memory")
; __device__ __forceinline__ int crow(int r, int hi) { return (r & 3) + 8 * (r >> 2) + 4 * hi; }
; #define MFMA32(a, b, c) __builtin_amdgcn_mfma_f32_32x32x16_bf16((a), (b), (c), 0, 0, 0)
; __device__ __forceinline__ void sb_wave(int bh, int qblk, int lane, const bf16_t* __restrict__ P1, const bf16_t* __restrict__ VT, bf16_t* __restrict__ ymix, LAS unsigned char* wl) {
;     ...
;         for (int i = 0; i < 4; ++i) { *(LAS v4u*)(wl + lK + i * 8 * 144) = rk[i]; *(LAS u32x2*)(wl + lV + i * 16 * 72) = (u32x2){rv[i].x, rv[i].y}; *(LAS u32x2*)(wl + lV + i * 16 * 72 + 8) = (u32x2){rv[i].z, rv[i].w}; }
;         { const int sn = (s0 >= 32) ? s0 - 32 : 0;
; #pragma unroll
;           for (int i = 0; i < 4; ++i) { rk[i] = *(const v4u*)(gK + (size_t)(sn + 8 * i) * L1P); rv[i] = *(const v4u*)(gV + (size_t)(16 * i) * M + sn); } }
;         WSYNC();
;         f32x16 acc;
; #pragma unroll
;         for (int r = 0; r < 16; ++r) acc[r] = 0.f;
; #pragma unroll
;         for (int kk = 0; kk < 4; ++kk) { const bf16x8 kf = *(const LAS bf16x8*)(wl + l31 * 144 + (16 * kk + 8 * hi) * 2); acc = MFMA32(kf, qf[kk], acc); }
;         const bool diag = (s0 == q0);
;         float bt[16], kp[16];
; #pragma unroll
;         for (int r = 0; r < 16; ++r) { const float ee = __builtin_amdgcn_exp2f(fminf(acc[r] * (-0.125f * 1.4426950408889634f), 100.f)); const float ri = __builtin_amdgcn_rcpf(1.f + ee);
;             float b_ = ri, k_ = ee * ri;
;             if (diag) { const bool valid = (s0 + crow(r, hi)) < t; b_ = valid ? b_ : 0.f; k_ = valid ? k_ : 1.f; }
;             bt[r] = b_; kp[r] = k_; }
.Lsb_tail:
	s_add_i32 s0, s18, s19
	s_sub_i32 s1, s0, 32
	s_cmp_lg_u32 s0, 0
	s_cselect_b32 s0, s1, 0
	s_ashr_i32 s1, s0, 31
	s_lshl_b64 s[2:3], s[0:1], 12
	v_lshl_add_u64 v[34:35], v[106:107], 0, s[2:3]
	s_or_b32 s2, s0, 8
	v_lshl_add_u64 v[74:75], s[0:1], 1, v[108:109]
	s_ashr_i32 s3, s2, 31
	s_lshl_b64 s[2:3], s[2:3], 12
	v_add_co_u32_e32 v40, vcc, s50, v74
	v_lshl_add_u64 v[38:39], v[106:107], 0, s[2:3]
	s_nop 0
	v_addc_co_u32_e32 v41, vcc, 0, v75, vcc
	global_load_dwordx4 v[46:49], v[34:35], off offset:1024
	s_nop 0
	global_load_dwordx4 v[34:37], v[74:75], off
	global_load_dwordx4 v[70:73], v[38:39], off offset:1024
	global_load_dwordx4 v[42:45], v[40:41], off
	s_or_b32 s2, s0, 16
	v_add_co_u32_e32 v40, vcc, s20, v74
	s_or_b32 s0, s0, 24
	s_ashr_i32 s3, s2, 31
	v_addc_co_u32_e32 v41, vcc, 0, v75, vcc
	s_ashr_i32 s1, s0, 31
	s_lshl_b64 s[2:3], s[2:3], 12
	s_lshl_b64 s[0:1], s[0:1], 12
	v_add_co_u32_e32 v74, vcc, s14, v74
	v_lshl_add_u64 v[38:39], v[106:107], 0, s[2:3]
	v_lshl_add_u64 v[76:77], v[106:107], 0, s[0:1]
	v_addc_co_u32_e32 v75, vcc, 0, v75, vcc
	global_load_dwordx4 v[66:69], v[38:39], off offset:1024
	s_nop 0
	global_load_dwordx4 v[38:41], v[40:41], off
	s_nop 0
	global_load_dwordx4 v[78:81], v[76:77], off offset:1024
	s_nop 0
	global_load_dwordx4 v[74:77], v[74:75], off
	s_sub_i32 s19, s19, 32
	s_add_i32 s0, s18, s19
	s_add_i32 s0, s0, 32
	s_cmp_lt_i32 s0, 32
	s_mov_b64 s[12:13], 0
	s_cselect_b64 s[48:49], -1, 0
	s_branch .LBB0_1569
.Lsb_nd_body:
	ds_write_b128 v119, v[46:49]
	v_add_u32_e32 v46, 0x1200, v120
	ds_write2_b64 v46, v[34:35], v[36:37] offset1:1
	ds_write_b128 v119, v[70:73] offset:1152
	v_add_u32_e32 v34, 0x1680, v120
	ds_write2_b64 v34, v[42:43], v[44:45] offset1:1
	ds_write_b128 v119, v[66:69] offset:2304
	v_add_u32_e32 v34, 0x1b00, v120
	ds_write2_b64 v34, v[38:39], v[40:41] offset1:1
	ds_write_b128 v119, v[78:81] offset:3456
	v_add_u32_e32 v34, 0x1f80, v120
	ds_write2_b64 v34, v[74:75], v[76:77] offset1:1
	s_waitcnt lgkmcnt(0)
	v_add_u32_e32 v70, v87, v86
	ds_read_b128 v[34:37], v70
	ds_read_b128 v[66:69], v70 offset:32
	s_waitcnt lgkmcnt(1)
	v_mfma_f32_32x32x16_bf16 v[34:49], v[34:37], v[50:53], 0
	s_mov_b64 s[48:49], -1
	s_waitcnt lgkmcnt(0)
	v_mfma_f32_32x32x16_bf16 v[34:49], v[66:69], v[54:57], v[34:49]
	ds_read_b128 v[66:69], v70 offset:64
	ds_read_b128 v[70:73], v70 offset:96
	s_waitcnt lgkmcnt(1)
	v_mfma_f32_32x32x16_bf16 v[34:49], v[66:69], v[58:61], v[34:49]
	v_add_u32_e32 v66, s19, v99
	s_waitcnt lgkmcnt(0)
	v_mfma_f32_32x32x16_bf16 v[34:49], v[70:73], v[62:65], v[34:49]
	s_nop 11
	v_mul_f32_e32 v35, 0xbe38aa3b, v35
	v_mul_f32_e32 v34, 0xbe38aa3b, v34
	v_min_f32_e32 v35, 0x42c80000, v35
	v_mul_f32_e32 v36, 0xbe38aa3b, v36
	v_min_f32_e32 v34, 0x42c80000, v34
	v_exp_f32_e32 v35, v35
	v_min_f32_e32 v36, 0x42c80000, v36
	v_exp_f32_e32 v34, v34
	v_exp_f32_e32 v36, v36
	v_mul_f32_e32 v37, 0xbe38aa3b, v37
	v_min_f32_e32 v37, 0x42c80000, v37
	v_add_f32_e32 v70, 1.0, v35
	v_exp_f32_e32 v69, v37
	v_add_f32_e32 v37, 1.0, v34
	v_rcp_f32_e32 v70, v70
	v_rcp_f32_e32 v37, v37
	v_add_f32_e32 v71, 1.0, v36
	v_rcp_f32_e32 v71, v71
	v_mul_f32_e32 v38, 0xbe38aa3b, v38
	v_min_f32_e32 v38, 0x42c80000, v38
	v_mul_f32_e32 v73, v35, v70
	v_exp_f32_e32 v38, v38
	v_mul_f32_e32 v34, v34, v37
	v_add_f32_e32 v68, 1.0, v69
	v_mul_f32_e32 v36, v36, v71
	v_rcp_f32_e32 v68, v68
	v_mov_b32_e32 v35, v34
	v_mov_b32_e32 v67, v70
	v_mov_b32_e32 v70, v71
	v_add_f32_e32 v71, 1.0, v38
	v_rcp_f32_e32 v71, v71
	v_mul_f32_e32 v34, v69, v68
	v_mov_b32_e32 v72, v37
	v_mov_b32_e32 v37, v73
	v_mov_b32_e32 v73, v34
	v_mul_f32_e32 v34, v38, v71
	v_mul_f32_e32 v38, 0xbe38aa3b, v39
	v_min_f32_e32 v38, 0x42c80000, v38
	v_exp_f32_e32 v38, v38
	s_nop 0
	v_add_f32_e32 v69, 1.0, v38
	v_mul_f32_e32 v39, 0xbe38aa3b, v40
	v_min_f32_e32 v39, 0x42c80000, v39
	v_rcp_f32_e32 v69, v69
	v_exp_f32_e32 v39, v39
	v_mul_f32_e32 v41, 0xbe38aa3b, v41
	v_min_f32_e32 v41, 0x42c80000, v41
	v_exp_f32_e32 v41, v41
	v_mul_f32_e32 v38, v38, v69
	v_add_f32_e32 v74, 1.0, v39
	v_rcp_f32_e32 v74, v74
	v_add_f32_e32 v75, 1.0, v41
	v_rcp_f32_e32 v75, v75
	v_mov_b32_e32 v40, v69
	v_mul_f32_e32 v39, v39, v74
	s_nop 1
	v_mov_b32_e32 v76, v39
	v_mul_f32_e32 v39, v41, v75
	v_mul_f32_e32 v41, 0xbe38aa3b, v42
	v_min_f32_e32 v41, 0x42c80000, v41
	v_exp_f32_e32 v41, v41
	v_mov_b32_e32 v69, v74
	v_add_f32_e32 v74, 1.0, v41
	v_rcp_f32_e32 v74, v74
	s_nop 1
	v_mov_b32_e32 v77, v39
	v_mul_f32_e32 v39, v41, v74
	v_mul_f32_e32 v41, 0xbe38aa3b, v43
	v_min_f32_e32 v41, 0x42c80000, v41
	v_exp_f32_e32 v41, v41
	v_mov_b32_e32 v42, v75
	v_add_f32_e32 v75, 1.0, v41
	v_rcp_f32_e32 v75, v75
	s_nop 1
	v_mov_b32_e32 v78, v39
	v_mul_f32_e32 v39, v41, v75
	v_mul_f32_e32 v41, 0xbe38aa3b, v44
	v_min_f32_e32 v41, 0x42c80000, v41
	v_exp_f32_e32 v41, v41
; #define LAS __attribute__((address_space(3)))
; #define WSYNC() asm volatile("s_waitcnt lgkmcnt(0)" ::: "memory")
; __device__ __forceinline__ int crow(int r, int hi) { return (r & 3) + 8 * (r >> 2) + 4 * hi; }
; __device__ __forceinline__ void sb_wave(int bh, int qblk, int lane, const bf16_t* __restrict__ P1, const bf16_t* __restrict__ VT, bf16_t* __restrict__ ymix, LAS unsigned char* wl) {
;     ...
; #pragma unroll
;         for (int r = 0; r < 16; ++r) { const float ee = __builtin_amdgcn_exp2f(fminf(acc[r] * (-0.125f * 1.4426950408889634f), 100.f)); const float ri = __builtin_amdgcn_rcpf(1.f + ee);
;             float b_ = ri, k_ = ee * ri;
;             if (diag) { const bool valid = (s0 + crow(r, hi)) < t; b_ = valid ? b_ : 0.f; k_ = valid ? k_ : 1.f; }
;             bt[r] = b_; kp[r] = k_; }
;         float e[16], T[4], U[4];
; #pragma unroll
;         for (int q = 0; q < 4; ++q) { e[4 * q + 3] = 1.f; e[4 * q + 2] = kp[4 * q + 3]; e[4 * q + 1] = e[4 * q + 2] * kp[4 * q + 2]; e[4 * q] = e[4 * q + 1] * kp[4 * q + 1]; T[q] = e[4 * q] * kp[4 * q]; }
; #pragma unroll
;         for (int q = 0; q < 4; ++q) U[q] = xhalf(T[q], hi);
;         { const float st2 = T[3], st1 = st2 * T[2], st0 = st1 * T[1]; const float su2 = U[3], su1 = su2 * U[2], su0 = su1 * U[1];
;           const float x0 = hi ? 1.f : U[0], x1 = hi ? 1.f : U[1], x2 = hi ? 1.f : U[2], x3 = hi ? 1.f : U[3];
;           const float off[4] = {cum * (st0 * su0 * x0), cum * (st1 * su1 * x1), cum * (st2 * su2 * x2), cum * x3};
; #pragma unroll
;           for (int r = 0; r < 16; ++r) acc[r] = bt[r] * (off[r >> 2] * e[r]);
;           cum *= (st0 * T[0]) * (su0 * U[0]); }
;         bf16x8 pf[2];
; #pragma unroll
;         for (int ks = 0; ks < 2; ++ks) pf[ks] = pack8(acc[8 * ks], acc[8 * ks + 1], acc[8 * ks + 2], acc[8 * ks + 3], acc[8 * ks + 4], acc[8 * ks + 5], acc[8 * ks + 6], acc[8 * ks + 7]);
; #pragma unroll
;         for (int dt = 0; dt < 2; ++dt)
; #pragma unroll
;             for (int ks = 0; ks < 2; ++ks) { const LAS unsigned char* vp = wl + 4608 + (32 * dt + l31) * 72 + (16 * ks + 4 * hi) * 2;
;                 const u32x2 x0 = *(const LAS u32x2*)vp, x1 = *(const LAS u32x2*)(vp + 16);
;                 v4u a; a.x = x0.x; a.y = x0.y; a.z = x1.x; a.w = x1.y; o[dt] = MFMA32(__builtin_bit_cast(bf16x8, a), pf[ks], o[dt]); }
;         WSYNC();
;         if (__all(cum < 1e-35f)) break;
	v_mov_b32_e32 v43, v74
	v_add_f32_e32 v74, 1.0, v41
	v_rcp_f32_e32 v74, v74
	s_nop 1
	v_mov_b32_e32 v79, v39
	v_mul_f32_e32 v39, v41, v74
	v_mul_f32_e32 v41, 0xbe38aa3b, v45
	v_min_f32_e32 v41, 0x42c80000, v41
	v_exp_f32_e32 v41, v41
	v_mov_b32_e32 v44, v75
	v_add_f32_e32 v75, 1.0, v41
	v_rcp_f32_e32 v75, v75
	s_nop 1
	v_mov_b32_e32 v80, v39
	v_mul_f32_e32 v39, v41, v75
	v_mul_f32_e32 v41, 0xbe38aa3b, v46
	v_min_f32_e32 v41, 0x42c80000, v41
	v_exp_f32_e32 v41, v41
	v_mov_b32_e32 v45, v74
	v_add_f32_e32 v74, 1.0, v41
	v_rcp_f32_e32 v74, v74
	s_nop 1
	v_mov_b32_e32 v81, v39
	v_mul_f32_e32 v39, v41, v74
	v_mul_f32_e32 v41, 0xbe38aa3b, v47
	v_min_f32_e32 v41, 0x42c80000, v41
	v_exp_f32_e32 v41, v41
	v_mov_b32_e32 v46, v75
	v_add_f32_e32 v75, 1.0, v41
	v_rcp_f32_e32 v75, v75
	s_nop 1
	v_mov_b32_e32 v104, v39
	v_mul_f32_e32 v39, v41, v75
	v_mul_f32_e32 v41, 0xbe38aa3b, v48
	v_min_f32_e32 v41, 0x42c80000, v41
	v_exp_f32_e32 v41, v41
	s_nop 0
	v_add_f32_e32 v48, 1.0, v41
	v_rcp_f32_e32 v48, v48
	s_nop 1
	v_mov_b32_e32 v125, v39
	v_mul_f32_e32 v39, v41, v48
	v_mul_f32_e32 v41, 0xbe38aa3b, v49
	v_min_f32_e32 v41, 0x42c80000, v41
	v_exp_f32_e32 v41, v41
	s_nop 0
	v_add_f32_e32 v49, 1.0, v41
	v_rcp_f32_e32 v49, v49
	s_nop 1
	v_mov_b32_e32 v126, v39
	v_mul_f32_e32 v39, v41, v49
	v_mov_b32_e32 v127, v48
	v_mul_f32_e32 v48, v81, v80
	v_mov_b32_e32 v128, v49
	v_mul_f32_e32 v41, v77, v76
	v_mul_f32_e32 v76, v38, v41
	v_mov_b32_e32 v66, v39
	v_mul_f32_e32 v47, v34, v76
	v_mul_f32_e32 v39, v73, v36
	v_mul_f32_e32 v49, v79, v48
	v_mov_b32_e32 v34, v47
	v_mov_b32_e32 v36, v47
	v_mul_f32_e32 v78, v78, v49
	v_mul_f32_e32 v79, v66, v126
	v_permlane32_swap_b32_e32 v34, v36
	v_mul_f32_e32 v80, v125, v79
	v_cndmask_b32_e64 v34, v34, v36, s[10:11]
	v_mov_b32_e32 v36, v78
	v_mov_b32_e32 v38, v78
	v_mul_f32_e32 v104, v104, v80
	s_nop 0
	v_permlane32_swap_b32_e32 v36, v38
	v_cndmask_b32_e64 v36, v36, v38, s[10:11]
	v_mov_b32_e32 v38, v104
	v_mov_b32_e32 v125, v104
	s_nop 1
	v_permlane32_swap_b32_e32 v38, v125
	v_cndmask_b32_e64 v38, v38, v125, s[10:11]
	v_mul_f32_e32 v78, v104, v78
	v_cndmask_b32_e64 v126, 1.0, v36, s[10:11]
	v_mul_f32_e32 v104, v104, v38
	v_mul_f32_e32 v104, v126, v104
	v_mul_f32_e32 v104, v101, v104
	v_cndmask_b32_e64 v129, 1.0, v38, s[10:11]
	v_mul_f32_e32 v49, v49, v104
	v_pk_mul_f32 v[36:37], v[36:37], v[38:39]
	v_mul_f32_e32 v126, v101, v129
	v_mul_f32_e32 v129, v43, v49
	v_mul_f32_e32 v43, v48, v104
	v_pk_mul_f32 v[48:49], v[36:37], v[34:35]
	v_cndmask_b32_e64 v125, 1.0, v34, s[10:11]
	v_mov_b32_e32 v34, v49
	v_mov_b32_e32 v35, v49
	s_nop 1
	v_permlane32_swap_b32_e32 v34, v35
	v_mul_f32_e32 v47, v47, v78
	v_mul_f32_e32 v130, v44, v43
	v_mul_f32_e32 v43, v81, v104
	v_mul_f32_e32 v104, v46, v104
	v_cndmask_b32_e64 v46, v34, v35, s[10:11]
	v_cndmask_b32_e64 v34, 1.0, v46, s[10:11]
	v_mul_f32_e32 v35, v48, v47
	v_mul_f32_e32 v34, v34, v35
	v_mul_f32_e32 v35, v36, v78
	v_mul_f32_e32 v81, v45, v43
	v_mul_f32_e32 v43, v126, v80
	v_mul_f32_e32 v34, v101, v34
	v_mul_f32_e32 v35, v125, v35
	v_mul_f32_e32 v74, v74, v43
	v_mul_f32_e32 v43, v126, v79
	v_mul_f32_e32 v38, v101, v35
	v_mul_f32_e32 v35, v37, v34
	v_mul_f32_e32 v75, v75, v43
	v_mul_f32_e32 v43, v72, v35
	v_mul_f32_e32 v35, v39, v34
	v_mul_f32_e32 v39, v67, v35
	v_mul_f32_e32 v35, v73, v34
	v_mul_f32_e32 v45, v68, v34
	v_mul_f32_e32 v34, v76, v38
	v_mul_f32_e32 v67, v71, v34
	v_mul_f32_e32 v34, v41, v38
	v_add_u32_e32 v68, 0x1000, v121
	v_mul_f32_e32 v44, v70, v35
	v_mul_f32_e32 v40, v40, v34
	ds_read2_b64 v[34:37], v68 offset0:64 offset1:66
	v_mul_f32_e32 v41, v77, v38
	v_mul_f32_e32 v41, v69, v41
	v_mul_f32_e32 v42, v42, v38
	v_cvt_pk_bf16_f32 v38, v43, v39
	v_cvt_pk_bf16_f32 v39, v44, v45
	v_cvt_pk_bf16_f32 v40, v67, v40
	v_cvt_pk_bf16_f32 v41, v41, v42
	ds_read2_b64 v[42:45], v68 offset0:68 offset1:70
	s_mov_b64 s[12:13], -1
	s_waitcnt lgkmcnt(1)
	v_mfma_f32_32x32x16_bf16 v[18:33], v[34:37], v[38:41], v[18:33]
	v_mul_f32_e32 v34, v126, v66
	v_mul_f32_e32 v37, v127, v34
	v_mul_f32_e32 v66, v128, v126
	v_cvt_pk_bf16_f32 v34, v129, v130
	v_cvt_pk_bf16_f32 v35, v81, v104
	v_cvt_pk_bf16_f32 v36, v74, v75
	v_cvt_pk_bf16_f32 v37, v37, v66
	v_add_u32_e32 v66, 0x1000, v122
	s_waitcnt lgkmcnt(0)
	v_mfma_f32_32x32x16_bf16 v[18:33], v[42:45], v[34:37], v[18:33]
	ds_read2_b64 v[42:45], v66 offset0:64 offset1:66
	s_waitcnt lgkmcnt(0)
	v_mfma_f32_32x32x16_bf16 v[2:17], v[42:45], v[38:41], v[2:17]
	ds_read2_b64 v[38:41], v66 offset0:68 offset1:70
	v_mul_f32_e64 v42, v48, v46
	v_mul_f32_e64 v43, v49, v47
	s_waitcnt lgkmcnt(0)
	v_mul_f32_e32 v42, v42, v43
	v_mul_f32_e32 v101, v101, v42
	s_waitcnt lgkmcnt(0)
	v_mfma_f32_32x32x16_bf16 v[2:17], v[38:41], v[34:37], v[2:17]
	v_cmp_gt_f32_e32 vcc, s51, v101
	s_cmp_lg_u64 vcc, exec
	s_cbranch_scc0 .LBB0_1569
	s_branch .Lsb_tail
